# PEER U/V group loops: group-start wait leaves the previous group's last store in flight (vmcnt(1)); full wait only on the slice-switch path
# speedup vs baseline: 1.0066x; 1.0066x over previous
.LBB0_1074:
	s_waitcnt vmcnt(1)
	v_readfirstlane_b32 s34, v190
	s_cmpk_lt_i32 s34, 0x4800
	s_mov_b64 s[36:37], -1
	s_cbranch_scc0 .LBB0_1080
	s_lshl_b32 s30, s33, 6
	v_mov_b32_e32 v190, 0
	s_and_saveexec_b64 s[36:37], s[6:7]
	s_cbranch_execz .LBB0_1077
	s_lshl_b64 s[38:39], s[30:31], 2
	s_add_u32 s38, s0, s38
	s_addc_u32 s39, s1, s39
	global_atomic_add v190, v179, v194, s[38:39] sc0

.LBB0_1080:
	s_and_b64 vcc, exec, s[36:37]
	s_cbranch_vccz .LBB0_1074
	s_mov_b64 s[34:35], -1
	s_cmp_eq_u32 s46, 7
	v_readfirstlane_b32 s33, v0
	v_readfirstlane_b32 s30, v0
	s_cbranch_scc1 .LBB0_1073
	s_add_i32 s30, s46, 1
	s_add_i32 s33, s30, s2
	s_and_b32 s33, s33, 7
	v_mov_b32_e32 v190, 0
	s_and_saveexec_b64 s[34:35], s[6:7]
	s_xor_b64 s[34:35], exec, s[34:35]
	s_cbranch_execz .LBB0_1072
	s_lshl_b32 s36, s33, 8
	s_waitcnt vmcnt(1)
	v_mov_b32_e32 v2, s36
	global_atomic_add v190, v2, v194, s[0:1] sc0
	s_waitcnt vmcnt(0)
	s_branch .LBB0_1072

.LBB0_1206:
	s_waitcnt vmcnt(1)
	v_readfirstlane_b32 s20, v216
	s_cmpk_lt_i32 s20, 0x4800
	s_mov_b64 s[22:23], -1
	s_cbranch_scc0 .LBB0_1212
	v_mov_b32_e32 v216, 0
	s_and_saveexec_b64 s[22:23], s[6:7]
	s_cbranch_execz .LBB0_1209
	v_lshlrev_b32_e32 v190, 6, v220
	v_lshlrev_b64 v[2:3], 2, v[190:191]
	v_lshl_add_u64 v[2:3], s[0:1], 0, v[2:3]
	global_atomic_add v216, v[2:3], v219, off sc0

.LBB0_1212:
	s_and_b64 vcc, exec, s[22:23]
	s_cbranch_vccz .LBB0_1206
	s_mov_b64 s[20:21], -1
	s_cmp_eq_u32 s40, 7
	v_readfirstlane_b32 s22, v0
	s_cbranch_scc1 .LBB0_1205
	s_add_i32 s22, s40, 1
	s_add_i32 s20, s22, s2
	s_and_b32 s23, s20, 7
	v_mov_b32_e32 v216, 0
	s_and_saveexec_b64 s[20:21], s[6:7]
	s_xor_b64 s[20:21], exec, s[20:21]
	s_cbranch_execz .LBB0_1204
	s_lshl_b32 s24, s23, 8
	v_mov_b32_e32 v2, s24
	global_atomic_add v216, v2, v219, s[0:1] sc0
	s_waitcnt vmcnt(0)
	s_branch .LBB0_1204

.LBB0_2239:
	s_waitcnt vmcnt(1)
	v_readfirstlane_b32 s16, v202
	s_cmpk_lt_i32 s16, 0x4800
	s_mov_b64 s[18:19], -1
	s_cbranch_scc0 .LBB0_2245
	v_mov_b32_e32 v202, 0
	s_and_saveexec_b64 s[18:19], s[6:7]
	s_cbranch_execz .LBB0_2242
	v_lshlrev_b32_e32 v182, 6, v206
	v_lshlrev_b64 v[2:3], 2, v[182:183]
	v_lshl_add_u64 v[2:3], s[0:1], 0, v[2:3]
	global_atomic_add v202, v[2:3], v205, off sc0

.LBB0_2245:
	s_and_b64 vcc, exec, s[18:19]
	s_cbranch_vccz .LBB0_2239
	s_mov_b64 s[16:17], -1
	s_cmp_eq_u32 s27, 7
	v_readfirstlane_b32 s18, v0
	s_cbranch_scc1 .LBB0_2238
	s_add_i32 s18, s27, 1
	s_add_i32 s16, s18, s2
	s_and_b32 s19, s16, 7
	v_mov_b32_e32 v202, 0
	s_and_saveexec_b64 s[16:17], s[6:7]
	s_xor_b64 s[16:17], exec, s[16:17]
	s_cbranch_execz .LBB0_2237
	s_lshl_b32 s20, s19, 8
	v_mov_b32_e32 v2, s20
	global_atomic_add v202, v2, v205, s[0:1] sc0
	s_waitcnt vmcnt(0)
	s_branch .LBB0_2237

.LBB0_2973:
	s_waitcnt vmcnt(1)
	v_readfirstlane_b32 s38, v190
	s_cmpk_lt_i32 s38, 0x4000
	s_mov_b64 s[40:41], -1
	s_cbranch_scc0 .LBB0_2979
	s_lshl_b32 s34, s33, 6
	v_mov_b32_e32 v190, 0
	s_and_saveexec_b64 s[40:41], s[8:9]
	s_cbranch_execz .LBB0_2976
	s_lshl_b64 s[42:43], s[34:35], 2
	s_add_u32 s42, s0, s42
	s_addc_u32 s43, s1, s43
	global_atomic_add v190, v179, v194, s[42:43] sc0

.LBB0_2979:
	s_and_b64 vcc, exec, s[40:41]
	s_cbranch_vccz .LBB0_2973
	s_mov_b64 s[38:39], -1
	s_cmp_eq_u32 s52, 7
	v_readfirstlane_b32 s33, v0
	v_readfirstlane_b32 s34, v0
	s_cbranch_scc1 .LBB0_2972
	s_add_i32 s34, s52, 1
	s_add_i32 s33, s34, s2
	s_and_b32 s33, s33, 7
	v_mov_b32_e32 v190, 0
	s_and_saveexec_b64 s[38:39], s[8:9]
	s_xor_b64 s[38:39], exec, s[38:39]
	s_cbranch_execz .LBB0_2971
	s_lshl_b32 s40, s33, 8
	s_waitcnt vmcnt(1)
	v_mov_b32_e32 v2, s40
	global_atomic_add v190, v2, v194, s[0:1] sc0
	s_waitcnt vmcnt(0)
	s_branch .LBB0_2971

.LBB0_3105:
	s_waitcnt vmcnt(1)
	v_readfirstlane_b32 s18, v202
	s_cmpk_lt_i32 s18, 0x4000
	s_mov_b64 s[20:21], -1
	s_cbranch_scc0 .LBB0_3111
	v_mov_b32_e32 v202, 0
	s_and_saveexec_b64 s[20:21], s[8:9]
	s_cbranch_execz .LBB0_3108
	v_lshlrev_b32_e32 v182, 6, v206
	v_lshlrev_b64 v[2:3], 2, v[182:183]
	v_lshl_add_u64 v[2:3], s[0:1], 0, v[2:3]
	global_atomic_add v202, v[2:3], v205, off sc0

.LBB0_3111:
	s_and_b64 vcc, exec, s[20:21]
	s_cbranch_vccz .LBB0_3105
	s_mov_b64 s[18:19], -1
	s_cmp_eq_u32 s29, 7
	v_readfirstlane_b32 s20, v0
	s_cbranch_scc1 .LBB0_3104
	s_add_i32 s20, s29, 1
	s_add_i32 s18, s20, s2
	s_and_b32 s21, s18, 7
	v_mov_b32_e32 v202, 0
	s_and_saveexec_b64 s[18:19], s[8:9]
	s_xor_b64 s[18:19], exec, s[18:19]
	s_cbranch_execz .LBB0_3103
	s_lshl_b32 s22, s21, 8
	v_mov_b32_e32 v2, s22
	global_atomic_add v202, v2, v205, s[0:1] sc0
	s_waitcnt vmcnt(0)
	s_branch .LBB0_3103

.LBB0_3958:
	s_waitcnt vmcnt(1)
	v_readfirstlane_b32 s30, v190
	s_cmpk_lt_i32 s30, 0x4000
	s_mov_b64 s[34:35], -1
	s_cbranch_scc0 .LBB0_3964
	s_lshl_b32 s26, s40, 6
	v_mov_b32_e32 v190, 0
	s_and_saveexec_b64 s[34:35], s[2:3]
	s_cbranch_execz .LBB0_3961
	s_lshl_b64 s[36:37], s[26:27], 2
	s_add_u32 s36, s0, s36
	s_addc_u32 s37, s1, s37
	global_atomic_add v190, v179, v194, s[36:37] sc0

.LBB0_3964:
	s_and_b64 vcc, exec, s[34:35]
	s_cbranch_vccz .LBB0_3958
	s_mov_b64 s[30:31], -1
	s_cmp_eq_u32 s43, 7
	v_readfirstlane_b32 s40, v0
	v_readfirstlane_b32 s26, v0
	s_cbranch_scc1 .LBB0_3957
	s_add_i32 s26, s43, 1
	s_add_i32 s30, s26, s33
	s_and_b32 s40, s30, 7
	v_mov_b32_e32 v190, 0
	s_and_saveexec_b64 s[30:31], s[2:3]
	s_xor_b64 s[30:31], exec, s[30:31]
	s_cbranch_execz .LBB0_3956
	s_lshl_b32 s34, s40, 8
	s_waitcnt vmcnt(1)
	v_mov_b32_e32 v2, s34
	global_atomic_add v190, v2, v194, s[0:1] sc0
	s_waitcnt vmcnt(0)
	s_branch .LBB0_3956

.LBB0_4090:
	s_waitcnt vmcnt(1)
	v_readfirstlane_b32 s12, v202
	s_cmpk_lt_i32 s12, 0x4000
	s_mov_b64 s[14:15], -1
	s_cbranch_scc0 .LBB0_4096
	v_mov_b32_e32 v202, 0
	s_and_saveexec_b64 s[14:15], s[2:3]
	s_cbranch_execz .LBB0_4093
	v_lshlrev_b32_e32 v182, 6, v206
	v_lshlrev_b64 v[2:3], 2, v[182:183]
	v_lshl_add_u64 v[2:3], s[0:1], 0, v[2:3]
	global_atomic_add v202, v[2:3], v205, off sc0

.LBB0_4096:
	s_and_b64 vcc, exec, s[14:15]
	s_cbranch_vccz .LBB0_4090
	s_mov_b64 s[12:13], -1
	s_cmp_eq_u32 s24, 7
	v_readfirstlane_b32 s14, v0
	s_cbranch_scc1 .LBB0_4089
	s_add_i32 s14, s24, 1
	s_add_i32 s12, s14, s22
	s_and_b32 s15, s12, 7
	v_mov_b32_e32 v202, 0
	s_and_saveexec_b64 s[12:13], s[2:3]
	s_xor_b64 s[12:13], exec, s[12:13]
	s_cbranch_execz .LBB0_4088
	s_lshl_b32 s16, s15, 8
	v_mov_b32_e32 v2, s16
	global_atomic_add v202, v2, v205, s[0:1] sc0
	s_waitcnt vmcnt(0)
	s_branch .LBB0_4088
